# shadow3: K-loop next-pointer selects (8 SALU) moved from P1 load segment into its MFMA block gaps; P5 a2 advance + both DMA addresses precomputed in P4 MFMA gaps
# speedup vs baseline: 1.0075x; 1.0075x over previous
.LBB0_522:
	s_add_i32 vcc_hi, 0, 0x10000
	v_add_u32_e32 v140, vcc_hi, v237
	s_waitcnt lgkmcnt(0)
	ds_read_b128 v[128:131], v140
	ds_read_b128 v[132:135], v140 offset:1024
	ds_read_b128 v[136:139], v140 offset:2048
	ds_read_b128 v[140:143], v140 offset:3072
	v_lshl_add_u64 v[176:177], s[72:73], 0, v[206:207]
	s_add_i32 m0, s93, 0xc000
	ds_read_b128 v[144:147], v240
	ds_read_b128 v[148:151], v240 offset:1024
	ds_read_b128 v[152:155], v240 offset:2048
	ds_read_b128 v[156:159], v240 offset:3072
	ds_read_b128 v[160:163], v240 offset:4096
	ds_read_b128 v[164:167], v240 offset:5120
	ds_read_b128 v[168:171], v240 offset:6144
	ds_read_b128 v[172:175], v240 offset:7168
	global_load_lds_dwordx4 v[176:177], off
	v_lshl_add_u64 v[176:177], s[72:73], 0, v[208:209]
	s_add_i32 m0, s93, 0xe000
	s_nop 0
	global_load_lds_dwordx4 v[176:177], off
	s_waitcnt lgkmcnt(8)
	s_barrier
	s_waitcnt lgkmcnt(0)
	v_mfma_f32_16x16x32_bf16 v[124:127], v[128:131], v[144:147], v[124:127]
	s_add_i32 vcc_lo, s74, 2
	v_mfma_f32_16x16x32_bf16 v[120:123], v[136:139], v[144:147], v[120:123]
	s_add_u32 s76, s72, 0x80
	v_mfma_f32_16x16x32_bf16 v[116:119], v[128:131], v[152:155], v[116:119]
	s_addc_u32 s75, s73, 0
	v_mfma_f32_16x16x32_bf16 v[112:115], v[136:139], v[152:155], v[112:115]
	s_cmp_eq_u32 s50, s74
	v_mfma_f32_16x16x32_bf16 v[100:103], v[128:131], v[160:163], v[100:103]
	s_cselect_b32 s74, s68, s76
	v_mfma_f32_16x16x32_bf16 v[96:99], v[136:139], v[160:163], v[96:99]
	s_cselect_b32 s75, s69, s75
	v_mfma_f32_16x16x32_bf16 v[84:87], v[128:131], v[168:171], v[84:87]
	s_cselect_b32 s77, s71, s79
	v_mfma_f32_16x16x32_bf16 v[80:83], v[136:139], v[168:171], v[80:83]
	s_cselect_b32 s76, s70, s78
	v_mfma_f32_16x16x32_bf16 v[124:127], v[132:135], v[148:151], v[124:127]
	s_add_i32 s31, 0, 0x14000
	v_mfma_f32_16x16x32_bf16 v[120:123], v[140:143], v[148:151], v[120:123]
	s_add_i32 vcc_hi, vcc_hi, s87
	v_mfma_f32_16x16x32_bf16 v[116:119], v[132:135], v[156:159], v[116:119]
	v_add_u32_e32 v188, s31, v237
	v_mfma_f32_16x16x32_bf16 v[112:115], v[140:143], v[156:159], v[112:115]
	v_lshl_add_u64 v[210:211], s[76:77], 0, v[196:197]
	v_mfma_f32_16x16x32_bf16 v[100:103], v[132:135], v[164:167], v[100:103]
	s_mov_b32 m0, vcc_hi
	v_mfma_f32_16x16x32_bf16 v[96:99], v[140:143], v[164:167], v[96:99]
	v_mfma_f32_16x16x32_bf16 v[84:87], v[132:135], v[172:175], v[84:87]
	v_mfma_f32_16x16x32_bf16 v[80:83], v[140:143], v[172:175], v[80:83]
	s_barrier
	ds_read_b128 v[176:179], v188
	ds_read_b128 v[180:183], v188 offset:1024
	ds_read_b128 v[184:187], v188 offset:2048
	ds_read_b128 v[188:191], v188 offset:3072
	global_load_lds_dwordx4 v[210:211], off
	v_lshl_add_u64 v[212:213], s[76:77], 0, v[200:201]
	s_add_i32 m0, vcc_hi, 0x2000
	s_nop 0
	global_load_lds_dwordx4 v[212:213], off
	s_barrier
	s_waitcnt lgkmcnt(0)
	v_mfma_f32_16x16x32_bf16 v[108:111], v[176:179], v[144:147], v[108:111]
	v_mfma_f32_16x16x32_bf16 v[104:107], v[184:187], v[144:147], v[104:107]
	v_mfma_f32_16x16x32_bf16 v[92:95], v[176:179], v[152:155], v[92:95]
	v_mfma_f32_16x16x32_bf16 v[88:91], v[184:187], v[152:155], v[88:91]
	v_mfma_f32_16x16x32_bf16 v[76:79], v[176:179], v[160:163], v[76:79]
	v_mfma_f32_16x16x32_bf16 v[72:75], v[184:187], v[160:163], v[72:75]
	v_mfma_f32_16x16x32_bf16 v[68:71], v[176:179], v[168:171], v[68:71]
	v_mfma_f32_16x16x32_bf16 v[64:67], v[184:187], v[168:171], v[64:67]
	v_mfma_f32_16x16x32_bf16 v[108:111], v[180:183], v[148:151], v[108:111]
	s_mov_b32 m0, s93
	v_mfma_f32_16x16x32_bf16 v[104:107], v[188:191], v[148:151], v[104:107]
	v_lshl_add_u64 v[214:215], s[74:75], 0, v[194:195]
	v_mfma_f32_16x16x32_bf16 v[92:95], v[180:183], v[156:159], v[92:95]
	v_mfma_f32_16x16x32_bf16 v[88:91], v[188:191], v[156:159], v[88:91]
	v_mfma_f32_16x16x32_bf16 v[76:79], v[180:183], v[164:167], v[76:79]
	v_mfma_f32_16x16x32_bf16 v[72:75], v[188:191], v[164:167], v[72:75]
	v_mfma_f32_16x16x32_bf16 v[68:71], v[180:183], v[172:175], v[68:71]
	v_mfma_f32_16x16x32_bf16 v[64:67], v[188:191], v[172:175], v[64:67]
	s_barrier
	ds_read_b128 v[144:147], v240 offset:16384
	ds_read_b128 v[148:151], v240 offset:17408
	ds_read_b128 v[152:155], v240 offset:18432
	ds_read_b128 v[156:159], v240 offset:19456
	ds_read_b128 v[160:163], v240 offset:20480
	ds_read_b128 v[164:167], v240 offset:21504
	ds_read_b128 v[168:171], v240 offset:22528
	ds_read_b128 v[172:175], v240 offset:23552
	global_load_lds_dwordx4 v[214:215], off
	v_lshl_add_u64 v[216:217], s[74:75], 0, v[198:199]
	s_mov_b32 m0, s54
	s_nop 0
	global_load_lds_dwordx4 v[216:217], off
	s_barrier
	s_waitcnt lgkmcnt(0)
	v_mfma_f32_16x16x32_bf16 v[60:63], v[128:131], v[144:147], v[60:63]
	v_mfma_f32_16x16x32_bf16 v[56:59], v[136:139], v[144:147], v[56:59]
	v_mfma_f32_16x16x32_bf16 v[52:55], v[128:131], v[152:155], v[52:55]
	v_mfma_f32_16x16x32_bf16 v[48:51], v[136:139], v[152:155], v[48:51]
	v_mfma_f32_16x16x32_bf16 v[36:39], v[128:131], v[160:163], v[36:39]
	v_mfma_f32_16x16x32_bf16 v[32:35], v[136:139], v[160:163], v[32:35]
	v_mfma_f32_16x16x32_bf16 v[20:23], v[128:131], v[168:171], v[20:23]
	v_mfma_f32_16x16x32_bf16 v[16:19], v[136:139], v[168:171], v[16:19]
	v_mfma_f32_16x16x32_bf16 v[60:63], v[132:135], v[148:151], v[60:63]
	s_add_u32 s76, s76, s20
	v_mfma_f32_16x16x32_bf16 v[56:59], v[140:143], v[148:151], v[56:59]
	s_addc_u32 s77, s77, 0
	v_mfma_f32_16x16x32_bf16 v[52:55], v[132:135], v[156:159], v[52:55]
	s_add_i32 s31, s31, s87
	v_mfma_f32_16x16x32_bf16 v[48:51], v[140:143], v[156:159], v[48:51]
	v_lshl_add_u64 v[218:219], s[76:77], 0, v[196:197]
	v_mfma_f32_16x16x32_bf16 v[36:39], v[132:135], v[164:167], v[36:39]
	s_mov_b32 m0, s31
	v_mfma_f32_16x16x32_bf16 v[32:35], v[140:143], v[164:167], v[32:35]
	v_lshl_add_u64 v[220:221], s[76:77], 0, v[200:201]
	v_mfma_f32_16x16x32_bf16 v[20:23], v[132:135], v[172:175], v[20:23]
	v_mfma_f32_16x16x32_bf16 v[16:19], v[140:143], v[172:175], v[16:19]
	s_barrier
	global_load_lds_dwordx4 v[218:219], off
	s_add_i32 m0, s31, 0x2000
	s_nop 0
	global_load_lds_dwordx4 v[220:221], off
	s_waitcnt vmcnt(6)
	s_barrier
	v_mfma_f32_16x16x32_bf16 v[44:47], v[176:179], v[144:147], v[44:47]
	v_mfma_f32_16x16x32_bf16 v[40:43], v[184:187], v[144:147], v[40:43]
	v_mfma_f32_16x16x32_bf16 v[28:31], v[176:179], v[152:155], v[28:31]
	v_mfma_f32_16x16x32_bf16 v[24:27], v[184:187], v[152:155], v[24:27]
	v_mfma_f32_16x16x32_bf16 v[12:15], v[176:179], v[160:163], v[12:15]
	v_mfma_f32_16x16x32_bf16 v[8:11], v[184:187], v[160:163], v[8:11]
	v_mfma_f32_16x16x32_bf16 v[4:7], v[176:179], v[168:171], v[4:7]
	v_mfma_f32_16x16x32_bf16 v[0:3], v[184:187], v[168:171], v[0:3]
	v_mfma_f32_16x16x32_bf16 v[44:47], v[180:183], v[148:151], v[44:47]
	s_add_i32 s31, 0, 0x18000
	v_mfma_f32_16x16x32_bf16 v[40:43], v[188:191], v[148:151], v[40:43]
	v_add_u32_e32 v140, s31, v237
	v_mfma_f32_16x16x32_bf16 v[28:31], v[180:183], v[156:159], v[28:31]
	s_add_u32 s74, s74, s20
	v_mfma_f32_16x16x32_bf16 v[24:27], v[188:191], v[156:159], v[24:27]
	s_addc_u32 s75, s75, 0
	v_mfma_f32_16x16x32_bf16 v[12:15], v[180:183], v[164:167], v[12:15]
	s_mov_b32 m0, s34
	v_mfma_f32_16x16x32_bf16 v[8:11], v[188:191], v[164:167], v[8:11]
	v_lshl_add_u64 v[176:177], s[74:75], 0, v[194:195]
	v_mfma_f32_16x16x32_bf16 v[4:7], v[180:183], v[172:175], v[4:7]
	v_lshl_add_u64 v[178:179], s[74:75], 0, v[198:199]
	v_mfma_f32_16x16x32_bf16 v[0:3], v[188:191], v[172:175], v[0:3]
	s_barrier
	ds_read_b128 v[128:131], v140
	ds_read_b128 v[132:135], v140 offset:1024
	ds_read_b128 v[136:139], v140 offset:2048
	ds_read_b128 v[140:143], v140 offset:3072
	ds_read_b128 v[144:147], v240 offset:32768
	ds_read_b128 v[148:151], v240 offset:33792
	ds_read_b128 v[152:155], v240 offset:34816
	ds_read_b128 v[156:159], v240 offset:35840
	ds_read_b128 v[160:163], v240 offset:36864
	ds_read_b128 v[164:167], v240 offset:37888
	ds_read_b128 v[168:171], v240 offset:38912
	ds_read_b128 v[172:175], v240 offset:39936
	global_load_lds_dwordx4 v[176:177], off
	s_mov_b32 m0, s35
	s_nop 0
	global_load_lds_dwordx4 v[178:179], off
	s_waitcnt lgkmcnt(8)
	s_barrier
	s_waitcnt lgkmcnt(0)
	v_mfma_f32_16x16x32_bf16 v[124:127], v[128:131], v[144:147], v[124:127]
	v_mfma_f32_16x16x32_bf16 v[120:123], v[136:139], v[144:147], v[120:123]
	v_mfma_f32_16x16x32_bf16 v[116:119], v[128:131], v[152:155], v[116:119]
	v_mfma_f32_16x16x32_bf16 v[112:115], v[136:139], v[152:155], v[112:115]
	v_mfma_f32_16x16x32_bf16 v[100:103], v[128:131], v[160:163], v[100:103]
	v_mfma_f32_16x16x32_bf16 v[96:99], v[136:139], v[160:163], v[96:99]
	v_mfma_f32_16x16x32_bf16 v[84:87], v[128:131], v[168:171], v[84:87]
	v_mfma_f32_16x16x32_bf16 v[80:83], v[136:139], v[168:171], v[80:83]
	v_mfma_f32_16x16x32_bf16 v[124:127], v[132:135], v[148:151], v[124:127]
	s_add_i32 s74, 0, 0x1c000
	v_mfma_f32_16x16x32_bf16 v[120:123], v[140:143], v[148:151], v[120:123]
	s_add_i32 s31, s31, s87
	v_mfma_f32_16x16x32_bf16 v[116:119], v[132:135], v[156:159], v[116:119]
	v_add_u32_e32 v188, s74, v237
	v_mfma_f32_16x16x32_bf16 v[112:115], v[140:143], v[156:159], v[112:115]
	v_lshl_add_u64 v[210:211], v[210:211], 0, s[60:61]
	v_mfma_f32_16x16x32_bf16 v[100:103], v[132:135], v[164:167], v[100:103]
	s_mov_b32 m0, s31
	v_mfma_f32_16x16x32_bf16 v[96:99], v[140:143], v[164:167], v[96:99]
	v_mfma_f32_16x16x32_bf16 v[84:87], v[132:135], v[172:175], v[84:87]
	v_mfma_f32_16x16x32_bf16 v[80:83], v[140:143], v[172:175], v[80:83]
	s_barrier
	ds_read_b128 v[176:179], v188
	ds_read_b128 v[180:183], v188 offset:1024
	ds_read_b128 v[184:187], v188 offset:2048
	ds_read_b128 v[188:191], v188 offset:3072
	global_load_lds_dwordx4 v[210:211], off
	v_lshl_add_u64 v[210:211], v[212:213], 0, s[60:61]
	s_add_i32 m0, s31, 0x2000
	s_nop 0
	global_load_lds_dwordx4 v[210:211], off
	s_barrier
	s_waitcnt lgkmcnt(0)
	v_mfma_f32_16x16x32_bf16 v[108:111], v[176:179], v[144:147], v[108:111]
	v_mfma_f32_16x16x32_bf16 v[104:107], v[184:187], v[144:147], v[104:107]
	v_mfma_f32_16x16x32_bf16 v[92:95], v[176:179], v[152:155], v[92:95]
	v_mfma_f32_16x16x32_bf16 v[88:91], v[184:187], v[152:155], v[88:91]
	v_mfma_f32_16x16x32_bf16 v[76:79], v[176:179], v[160:163], v[76:79]
	v_mfma_f32_16x16x32_bf16 v[72:75], v[184:187], v[160:163], v[72:75]
	v_mfma_f32_16x16x32_bf16 v[68:71], v[176:179], v[168:171], v[68:71]
	v_mfma_f32_16x16x32_bf16 v[64:67], v[184:187], v[168:171], v[64:67]
	v_mfma_f32_16x16x32_bf16 v[108:111], v[180:183], v[148:151], v[108:111]
	s_mov_b32 m0, s97
	v_mfma_f32_16x16x32_bf16 v[104:107], v[188:191], v[148:151], v[104:107]
	v_lshl_add_u64 v[210:211], v[214:215], 0, s[60:61]
	v_mfma_f32_16x16x32_bf16 v[92:95], v[180:183], v[156:159], v[92:95]
	v_mfma_f32_16x16x32_bf16 v[88:91], v[188:191], v[156:159], v[88:91]
	v_mfma_f32_16x16x32_bf16 v[76:79], v[180:183], v[164:167], v[76:79]
	v_mfma_f32_16x16x32_bf16 v[72:75], v[188:191], v[164:167], v[72:75]
	v_mfma_f32_16x16x32_bf16 v[68:71], v[180:183], v[172:175], v[68:71]
	v_mfma_f32_16x16x32_bf16 v[64:67], v[188:191], v[172:175], v[64:67]
	s_barrier
	ds_read_b128 v[144:147], v240 offset:49152
	ds_read_b128 v[148:151], v240 offset:50176
	ds_read_b128 v[152:155], v240 offset:51200
	ds_read_b128 v[156:159], v240 offset:52224
	ds_read_b128 v[160:163], v240 offset:53248
	ds_read_b128 v[164:167], v240 offset:54272
	ds_read_b128 v[168:171], v240 offset:55296
	ds_read_b128 v[172:175], v240 offset:56320
	global_load_lds_dwordx4 v[210:211], off
	v_lshl_add_u64 v[210:211], v[216:217], 0, s[60:61]
	s_mov_b32 m0, s36
	s_nop 0
	global_load_lds_dwordx4 v[210:211], off
	s_barrier
	s_waitcnt lgkmcnt(0)
	v_mfma_f32_16x16x32_bf16 v[60:63], v[128:131], v[144:147], v[60:63]
	v_mfma_f32_16x16x32_bf16 v[56:59], v[136:139], v[144:147], v[56:59]
	v_mfma_f32_16x16x32_bf16 v[52:55], v[128:131], v[152:155], v[52:55]
	v_mfma_f32_16x16x32_bf16 v[48:51], v[136:139], v[152:155], v[48:51]
	v_mfma_f32_16x16x32_bf16 v[36:39], v[128:131], v[160:163], v[36:39]
	v_mfma_f32_16x16x32_bf16 v[32:35], v[136:139], v[160:163], v[32:35]
	v_mfma_f32_16x16x32_bf16 v[20:23], v[128:131], v[168:171], v[20:23]
	v_mfma_f32_16x16x32_bf16 v[16:19], v[136:139], v[168:171], v[16:19]
	v_mfma_f32_16x16x32_bf16 v[60:63], v[132:135], v[148:151], v[60:63]
	s_add_i32 s31, s74, s87
	v_mfma_f32_16x16x32_bf16 v[56:59], v[140:143], v[148:151], v[56:59]
	v_lshl_add_u64 v[128:129], v[218:219], 0, s[60:61]
	v_mfma_f32_16x16x32_bf16 v[52:55], v[132:135], v[156:159], v[52:55]
	s_mov_b32 m0, s31
	v_mfma_f32_16x16x32_bf16 v[48:51], v[140:143], v[156:159], v[48:51]
	v_mfma_f32_16x16x32_bf16 v[36:39], v[132:135], v[164:167], v[36:39]
	v_mfma_f32_16x16x32_bf16 v[32:35], v[140:143], v[164:167], v[32:35]
	v_mfma_f32_16x16x32_bf16 v[20:23], v[132:135], v[172:175], v[20:23]
	v_mfma_f32_16x16x32_bf16 v[16:19], v[140:143], v[172:175], v[16:19]
	s_barrier
	s_nop 0
	global_load_lds_dwordx4 v[128:129], off
	v_lshl_add_u64 v[128:129], v[220:221], 0, s[60:61]
	s_add_i32 m0, s31, 0x2000
	s_nop 0
	global_load_lds_dwordx4 v[128:129], off
	s_waitcnt vmcnt(6)
	s_barrier
	v_mfma_f32_16x16x32_bf16 v[44:47], v[176:179], v[144:147], v[44:47]
	v_mfma_f32_16x16x32_bf16 v[40:43], v[184:187], v[144:147], v[40:43]
	v_mfma_f32_16x16x32_bf16 v[28:31], v[176:179], v[152:155], v[28:31]
	v_mfma_f32_16x16x32_bf16 v[24:27], v[184:187], v[152:155], v[24:27]
	v_mfma_f32_16x16x32_bf16 v[12:15], v[176:179], v[160:163], v[12:15]
	v_mfma_f32_16x16x32_bf16 v[8:11], v[184:187], v[160:163], v[8:11]
	v_mfma_f32_16x16x32_bf16 v[4:7], v[176:179], v[168:171], v[4:7]
	v_mfma_f32_16x16x32_bf16 v[0:3], v[184:187], v[168:171], v[0:3]
	v_mfma_f32_16x16x32_bf16 v[44:47], v[180:183], v[148:151], v[44:47]
	s_add_u32 s72, s72, 0x100
	v_mfma_f32_16x16x32_bf16 v[40:43], v[188:191], v[148:151], v[40:43]
	s_addc_u32 s73, s73, 0
	v_mfma_f32_16x16x32_bf16 v[28:31], v[180:183], v[156:159], v[28:31]
	s_add_u32 s78, s78, 0x100
	v_mfma_f32_16x16x32_bf16 v[24:27], v[188:191], v[156:159], v[24:27]
	s_addc_u32 s79, s79, 0
	v_mfma_f32_16x16x32_bf16 v[12:15], v[180:183], v[164:167], v[12:15]
	s_cmp_ge_u32 vcc_lo, s30
	v_mfma_f32_16x16x32_bf16 v[8:11], v[188:191], v[164:167], v[8:11]
	s_mov_b32 s74, vcc_lo
	v_mfma_f32_16x16x32_bf16 v[4:7], v[180:183], v[172:175], v[4:7]
	v_mfma_f32_16x16x32_bf16 v[0:3], v[188:191], v[172:175], v[0:3]
	s_barrier
	s_cbranch_scc0 .LBB0_522
	s_cmp_lt_i32 s91, 0
	s_mov_b64 s[72:73], -1
	s_cbranch_scc0 .LBB0_716
	s_lshl_b32 s78, s46, 8
	s_cmp_lt_i32 s81, 2
	s_cbranch_scc1 .LBB0_582
	s_cmp_lt_i32 s81, 3
	s_cbranch_scc1 .LBB0_579
	s_cmp_lg_u32 s81, 3
	s_cbranch_scc0 .LBB0_544
	v_lshl_or_b32 v128, s19, 7, v238
	v_ashrrev_i32_e32 v129, 31, v128
	v_lshl_add_u64 v[144:145], v[128:129], 1, s[24:25]
	v_and_b32_e32 v129, 64, v231
	v_xor_b32_e32 v128, 16, v231
	v_add_u32_e32 v129, 64, v129
	v_cmp_lt_i32_e32 vcc, v128, v129
	v_add_u32_e32 v146, s78, v202
	v_ashrrev_i32_e32 v147, 31, v146
	v_cndmask_b32_e32 v128, v231, v128, vcc
	v_lshlrev_b32_e32 v167, 2, v128
	v_xor_b32_e32 v128, 32, v231
	v_cmp_lt_i32_e32 vcc, v128, v129
	v_or_b32_e32 v156, 16, v146
	v_ashrrev_i32_e32 v157, 31, v156
	v_cndmask_b32_e32 v128, v231, v128, vcc
	v_lshlrev_b32_e32 v166, 2, v128
	v_lshlrev_b64 v[128:129], 12, v[146:147]
	v_lshl_add_u64 v[160:161], v[144:145], 0, v[128:129]
	global_load_dwordx4 v[140:143], v[160:161], off
	v_or_b32_e32 v152, 32, v146
	v_lshlrev_b64 v[128:129], 12, v[156:157]
	v_ashrrev_i32_e32 v153, 31, v152
	v_or_b32_e32 v148, 48, v146
	v_lshl_add_u64 v[158:159], v[144:145], 0, v[128:129]
	v_lshlrev_b64 v[128:129], 12, v[152:153]
	v_ashrrev_i32_e32 v149, 31, v148
	v_lshl_add_u64 v[154:155], v[144:145], 0, v[128:129]
	v_lshlrev_b64 v[128:129], 12, v[148:149]
	v_lshl_add_u64 v[150:151], v[144:145], 0, v[128:129]
	global_load_dwordx4 v[136:139], v[158:159], off
	global_load_dwordx4 v[132:135], v[154:155], off
	global_load_dwordx4 v[128:131], v[150:151], off
	v_mul_f32_e32 v163, 0xbfb8aa3b, v104
	v_exp_f32_e32 v163, v163
	v_mul_f32_e32 v162, 0xbfb8aa3b, v108
	v_exp_f32_e32 v162, v162
	v_add_f32_e32 v163, 1.0, v163
	v_rcp_f32_e32 v164, v163
	v_mul_f32_e32 v163, 0xbfb8aa3b, v109
	v_exp_f32_e32 v163, v163
	v_add_f32_e32 v162, 1.0, v162
	v_rcp_f32_e32 v162, v162
	v_add_f32_e32 v163, 1.0, v163
	v_rcp_f32_e32 v163, v163
	s_waitcnt vmcnt(0)
	v_lshlrev_b32_e32 v168, 16, v140
	v_and_b32_e32 v169, 0xffff0000, v140
	v_mul_f32_e32 v140, 0xbfb8aa3b, v105
	v_exp_f32_e32 v140, v140
	v_pk_fma_f32 v[162:163], v[162:163], v[124:125], v[168:169]
	v_lshlrev_b32_e32 v168, 16, v142
	v_and_b32_e32 v169, 0xffff0000, v142
	v_add_f32_e32 v140, 1.0, v140
	v_rcp_f32_e32 v165, v140
	v_mul_f32_e32 v140, 0xbfb8aa3b, v110
	v_exp_f32_e32 v140, v140
	v_mul_f32_e32 v142, 0xbfb8aa3b, v111
	v_pk_fma_f32 v[164:165], v[164:165], v[120:121], v[168:169]
	v_lshlrev_b32_e32 v170, 16, v141
	v_add_f32_e32 v140, 1.0, v140
	v_rcp_f32_e32 v168, v140
	v_mul_f32_e32 v140, 0xbfb8aa3b, v106
	v_and_b32_e32 v171, 0xffff0000, v141
	v_mul_f32_e32 v141, 0xbfb8aa3b, v107
	v_exp_f32_e32 v140, v140
	v_exp_f32_e32 v142, v142
	v_exp_f32_e32 v141, v141
	v_add_f32_e32 v140, 1.0, v140
	v_add_f32_e32 v142, 1.0, v142
	v_add_f32_e32 v141, 1.0, v141
	v_rcp_f32_e32 v140, v140
	v_rcp_f32_e32 v169, v142
	v_rcp_f32_e32 v141, v141
	v_lshlrev_b32_e32 v142, 16, v143
	v_and_b32_e32 v143, 0xffff0000, v143
	v_pk_fma_f32 v[168:169], v[168:169], v[126:127], v[170:171]
	v_pk_fma_f32 v[170:171], v[140:141], v[122:123], v[142:143]
	v_cvt_pk_bf16_f32 v140, v162, v163
	v_cvt_pk_bf16_f32 v141, v168, v169
	v_cvt_pk_bf16_f32 v142, v164, v165
	v_cvt_pk_bf16_f32 v143, v170, v171
	global_store_dwordx4 v[160:161], v[140:143], off
	v_pk_mul_f32 v[160:161], v[164:165], v[164:165]
	s_nop 0
	v_pk_mul_f32 v[140:141], v[162:163], v[162:163]
	v_pk_mul_f32 v[142:143], v[168:169], v[168:169]
	v_add_f32_e32 v140, v140, v141
	v_add_f32_e32 v142, v142, v143
	v_pk_mul_f32 v[162:163], v[170:171], v[170:171]
	v_add_f32_e32 v140, v140, v142
	v_add_f32_e32 v141, v160, v161
	v_add_f32_e32 v162, v162, v163
	v_add_f32_e32 v140, v141, v140
	v_add_f32_e32 v140, v162, v140
	v_mov_b32_e32 v141, v140
	s_nop 1
	v_permlane16_swap_b32_e32 v141, v140
	s_waitcnt lgkmcnt(0)
	v_add_f32_e32 v140, v140, v141
	v_mov_b32_e32 v141, v140
	s_nop 1
	v_permlane32_swap_b32_e32 v141, v140
	s_and_saveexec_b64 s[72:73], s[6:7]
	s_cbranch_execz .LBB0_529
	s_waitcnt lgkmcnt(0)
	v_add_f32_e32 v142, v140, v141
	s_lshl_b32 s74, s19, 2
	v_lshlrev_b64 v[140:141], 8, v[146:147]
	s_ashr_i32 s75, s74, 31
	v_lshl_add_u64 v[140:141], s[26:27], 0, v[140:141]
	v_lshl_add_u64 v[140:141], s[74:75], 2, v[140:141]
	s_lshl_b32 s50, s37, 2
	v_lshl_add_u64 v[140:141], v[140:141], 0, s[50:51]
	global_store_dword v[140:141], v142, off
